# out-proj epilogue: both residual batches loaded up front (second batch hoisted into free registers), one wait instead of two
# baseline (speedup 1.0000x reference)
.LBB0_581:
	v_lshl_add_u32 v172, s64, 8, v176
	v_lshl_or_b32 v170, s63, 8, v189
	v_ashrrev_i32_e32 v171, 31, v170
	v_ashrrev_i32_e32 v173, 31, v172
	v_lshl_add_u64 v[168:169], v[170:171], 1, s[16:17]
	v_add_u32_e32 v206, 0x80, v172
	v_ashrrev_i32_e32 v207, 31, v206
	v_lshlrev_b64 v[240:241], 12, v[206:207]
	v_lshl_add_u64 v[240:241], v[168:169], 0, v[240:241]
	global_load_dwordx4 v[208:211], v[240:241], off
	global_load_dwordx4 v[212:215], v[240:241], off offset:256
	v_add_u32_e32 v206, 0x90, v172
	v_ashrrev_i32_e32 v207, 31, v206
	v_lshlrev_b64 v[240:241], 12, v[206:207]
	v_lshl_add_u64 v[240:241], v[168:169], 0, v[240:241]
	global_load_dwordx4 v[216:219], v[240:241], off
	global_load_dwordx4 v[220:223], v[240:241], off offset:256
	v_add_u32_e32 v206, 0xa0, v172
	v_ashrrev_i32_e32 v207, 31, v206
	v_lshlrev_b64 v[240:241], 12, v[206:207]
	v_lshl_add_u64 v[240:241], v[168:169], 0, v[240:241]
	global_load_dwordx4 v[224:227], v[240:241], off
	global_load_dwordx4 v[228:231], v[240:241], off offset:256
	v_add_u32_e32 v206, 0xb0, v172
	v_ashrrev_i32_e32 v207, 31, v206
	v_lshlrev_b64 v[240:241], 12, v[206:207]
	v_lshl_add_u64 v[240:241], v[168:169], 0, v[240:241]
	global_load_dwordx4 v[232:235], v[240:241], off
	global_load_dwordx4 v[236:239], v[240:241], off offset:256
	v_lshlrev_b64 v[118:119], 12, v[172:173]
	v_or_b32_e32 v180, 16, v172
	v_lshl_add_u64 v[118:119], v[168:169], 0, v[118:119]
	v_ashrrev_i32_e32 v181, 31, v180
	global_load_dwordx4 v[202:205], v[118:119], off
	global_load_dwordx4 v[154:157], v[118:119], off offset:256
	v_lshlrev_b64 v[118:119], 12, v[180:181]
	v_or_b32_e32 v178, 32, v172
	v_lshl_add_u64 v[118:119], v[168:169], 0, v[118:119]
	v_ashrrev_i32_e32 v179, 31, v178
	global_load_dwordx4 v[150:153], v[118:119], off
	global_load_dwordx4 v[146:149], v[118:119], off offset:256
	v_lshlrev_b64 v[118:119], 12, v[178:179]
	v_or_b32_e32 v174, 48, v172
	v_lshl_add_u64 v[118:119], v[168:169], 0, v[118:119]
	v_ashrrev_i32_e32 v175, 31, v174
	global_load_dwordx4 v[142:145], v[118:119], off
	global_load_dwordx4 v[138:141], v[118:119], off offset:256
	v_lshlrev_b64 v[118:119], 12, v[174:175]
	v_lshl_add_u64 v[118:119], v[168:169], 0, v[118:119]
	global_load_dwordx4 v[126:129], v[118:119], off
	s_nop 0
	global_load_dwordx4 v[118:121], v[118:119], off offset:256
	v_cndmask_b32_e64 v182, 0, 1, s[38:39]
	v_lshlrev_b64 v[186:187], 11, v[172:173]
	v_cmp_ne_u32_e64 s[4:5], 1, v182
	v_lshl_add_u64 v[182:183], v[186:187], 0, v[170:171]
	s_andn2_b64 vcc, exec, s[38:39]
	s_waitcnt vmcnt(0)
	s_nop 0
	v_lshlrev_b32_e32 v184, 16, v202
	v_and_b32_e32 v185, 0xffff0000, v202
	v_lshlrev_b32_e32 v192, 16, v203
	v_and_b32_e32 v193, 0xffff0000, v203
	v_lshlrev_b32_e32 v202, 16, v204
	v_and_b32_e32 v203, 0xffff0000, v204
	v_lshlrev_b32_e32 v204, 16, v205
	v_and_b32_e32 v205, 0xffff0000, v205
	v_pk_add_f32 v[136:137], v[136:137], v[192:193]
	v_pk_add_f32 v[134:135], v[134:135], v[184:185]
	v_pk_add_f32 v[132:133], v[132:133], v[204:205]
	v_pk_add_f32 v[130:131], v[130:131], v[202:203]
	v_lshl_add_u64 v[184:185], v[182:183], 2, s[24:25]
	s_cbranch_vccnz .LBB0_583
	global_store_dwordx4 v[184:185], v[134:137], off
	global_store_dwordx4 v[184:185], v[130:133], off offset:16

.LBB0_621:
	s_or_b64 exec, exec, s[50:51]
	v_add_u32_e32 v100, 0x80, v172
	v_ashrrev_i32_e32 v101, 31, v100
	s_waitcnt lgkmcnt(0)
	v_add_u32_e32 v98, 0x90, v172
	v_ashrrev_i32_e32 v99, 31, v98
	v_add_u32_e32 v96, 0xa0, v172
	v_ashrrev_i32_e32 v97, 31, v96
	v_add_u32_e32 v94, 0xb0, v172
	v_ashrrev_i32_e32 v95, 31, v94
	v_mov_b64_e32 v[108:109], v[208:209]
	v_mov_b64_e32 v[110:111], v[210:211]
	v_mov_b64_e32 v[90:91], v[212:213]
	v_mov_b64_e32 v[92:93], v[214:215]
	v_mov_b64_e32 v[86:87], v[216:217]
	v_mov_b64_e32 v[88:89], v[218:219]
	v_mov_b64_e32 v[82:83], v[220:221]
	v_mov_b64_e32 v[84:85], v[222:223]
	v_mov_b64_e32 v[78:79], v[224:225]
	v_mov_b64_e32 v[80:81], v[226:227]
	v_mov_b64_e32 v[74:75], v[228:229]
	v_mov_b64_e32 v[76:77], v[230:231]
	v_mov_b64_e32 v[70:71], v[232:233]
	v_mov_b64_e32 v[72:73], v[234:235]
	v_mov_b64_e32 v[66:67], v[236:237]
	v_mov_b64_e32 v[68:69], v[238:239]
	v_lshlrev_b64 v[106:107], 11, v[100:101]
	v_lshl_add_u64 v[102:103], v[106:107], 0, v[170:171]
	s_and_b64 vcc, exec, s[4:5]
	s_nop 0
	v_lshlrev_b32_e32 v104, 16, v108
	v_and_b32_e32 v105, 0xffff0000, v108
	v_lshlrev_b32_e32 v108, 16, v109
	v_and_b32_e32 v109, 0xffff0000, v109
	v_lshlrev_b32_e32 v112, 16, v110
	v_and_b32_e32 v113, 0xffff0000, v110
	v_lshlrev_b32_e32 v110, 16, v111
	v_and_b32_e32 v111, 0xffff0000, v111
	v_pk_add_f32 v[64:65], v[64:65], v[108:109]
	v_pk_add_f32 v[62:63], v[62:63], v[104:105]
	v_pk_add_f32 v[60:61], v[60:61], v[110:111]
	v_pk_add_f32 v[58:59], v[58:59], v[112:113]
	v_lshl_add_u64 v[104:105], v[102:103], 2, s[24:25]
	s_cbranch_vccnz .LBB0_623
	global_store_dwordx4 v[104:105], v[62:65], off
	global_store_dwordx4 v[104:105], v[58:61], off offset:16
